# post_z head-norm slab: consecutive norm items prefetch the next item's 32 rows into a second register set (register software pipeline across items)
# speedup vs baseline: 1.0039x; 1.0039x over previous
; #define VBID ((int)(blockIdx.x * 2) + HALF())
; DI void post_z(const Params& p, int layer) {
;     ...
;   {
;     const float* part = (const float*)(p.ws + O_HID);
;     float* bias = (float*)(p.ws + O_BIAS);
;     const int idx = VBID * 256 + tid_;
;     if (idx < 512) {
;       const int kv = idx >> 8, n = idx & 255;
;       float a = 0.f;
;       for (int kc = 0; kc < 64; ++kc) a += part[(kv * 64 + kc) * 256 + n];
;       bias[idx] = a;
;     }
;   }
.LBB0_181:
	s_or_b64 exec, exec, s[0:1]
	v_readfirstlane_b32 s0, v196
	s_and_b32 s0, s0, 0xffffff00
	v_readlane_b32 s1, v252, 9
	v_and_b32_e32 v0, 0xff, v196
	s_add_i32 s0, s0, s1
	s_barrier
	s_mov_b32 s90, 0
	s_nop 0
	v_add_u32_e32 v2, s0, v0
	s_movk_i32 s0, 0x200
	v_cmp_gt_i32_e32 vcc, s0, v2
	s_and_saveexec_b64 s[0:1], vcc
	s_cbranch_execz .LBB0_185
	v_and_b32_e32 v3, 0xff, v0
	v_lshlrev_b32_e32 v4, 6, v2
	s_movk_i32 s2, 0xc000
	v_and_or_b32 v3, v4, s2, v3
	v_mov_b32_e32 v6, 0
	s_mov_b32 s2, 0
	v_lshlrev_b32_e32 v4, 2, v3
	v_mov_b32_e32 v5, v4
	global_load_dword v68, v5, s[26:27]
	global_load_dword v69, v5, s[26:27] offset:1024
	global_load_dword v70, v5, s[26:27] offset:2048
	global_load_dword v71, v5, s[26:27] offset:3072
	v_add_u32_e32 v5, 0x1000, v4
	global_load_dword v72, v5, s[26:27]
	global_load_dword v73, v5, s[26:27] offset:1024
	global_load_dword v74, v5, s[26:27] offset:2048
	global_load_dword v75, v5, s[26:27] offset:3072
	v_add_u32_e32 v5, 0x2000, v4
	global_load_dword v76, v5, s[26:27]
	global_load_dword v77, v5, s[26:27] offset:1024
	global_load_dword v78, v5, s[26:27] offset:2048
	global_load_dword v79, v5, s[26:27] offset:3072
	v_add_u32_e32 v5, 0x3000, v4
	global_load_dword v80, v5, s[26:27]
	global_load_dword v81, v5, s[26:27] offset:1024
	global_load_dword v82, v5, s[26:27] offset:2048
	global_load_dword v83, v5, s[26:27] offset:3072
	v_add_u32_e32 v5, 0x4000, v4
	global_load_dword v84, v5, s[26:27]
	global_load_dword v85, v5, s[26:27] offset:1024
	global_load_dword v86, v5, s[26:27] offset:2048
	global_load_dword v87, v5, s[26:27] offset:3072
	v_add_u32_e32 v5, 0x5000, v4
	global_load_dword v88, v5, s[26:27]
	global_load_dword v89, v5, s[26:27] offset:1024
	global_load_dword v90, v5, s[26:27] offset:2048
	global_load_dword v91, v5, s[26:27] offset:3072
	v_add_u32_e32 v5, 0x6000, v4
	global_load_dword v92, v5, s[26:27]
	global_load_dword v93, v5, s[26:27] offset:1024
	global_load_dword v94, v5, s[26:27] offset:2048
	global_load_dword v95, v5, s[26:27] offset:3072
	v_add_u32_e32 v5, 0x7000, v4
	global_load_dword v96, v5, s[26:27]
	global_load_dword v97, v5, s[26:27] offset:1024
	global_load_dword v98, v5, s[26:27] offset:2048
	global_load_dword v99, v5, s[26:27] offset:3072
	v_add_u32_e32 v5, 0x8000, v4
	global_load_dword v100, v5, s[26:27]
	global_load_dword v101, v5, s[26:27] offset:1024
	global_load_dword v102, v5, s[26:27] offset:2048
	global_load_dword v103, v5, s[26:27] offset:3072
	v_add_u32_e32 v5, 0x9000, v4
	global_load_dword v104, v5, s[26:27]
	global_load_dword v105, v5, s[26:27] offset:1024
	global_load_dword v106, v5, s[26:27] offset:2048
	global_load_dword v107, v5, s[26:27] offset:3072
	v_add_u32_e32 v5, 0xa000, v4
	global_load_dword v108, v5, s[26:27]
	global_load_dword v109, v5, s[26:27] offset:1024
	global_load_dword v110, v5, s[26:27] offset:2048
	global_load_dword v111, v5, s[26:27] offset:3072
	v_add_u32_e32 v5, 0xb000, v4
	global_load_dword v112, v5, s[26:27]
	global_load_dword v113, v5, s[26:27] offset:1024
	global_load_dword v114, v5, s[26:27] offset:2048
	global_load_dword v115, v5, s[26:27] offset:3072
	v_add_u32_e32 v5, 0xc000, v4
	global_load_dword v116, v5, s[26:27]
	global_load_dword v117, v5, s[26:27] offset:1024
	global_load_dword v118, v5, s[26:27] offset:2048
	global_load_dword v119, v5, s[26:27] offset:3072
	v_add_u32_e32 v5, 0xd000, v4
	global_load_dword v120, v5, s[26:27]
	global_load_dword v121, v5, s[26:27] offset:1024
	global_load_dword v122, v5, s[26:27] offset:2048
	global_load_dword v123, v5, s[26:27] offset:3072
	v_add_u32_e32 v5, 0xe000, v4
	global_load_dword v124, v5, s[26:27]
	global_load_dword v125, v5, s[26:27] offset:1024
	global_load_dword v126, v5, s[26:27] offset:2048
	global_load_dword v127, v5, s[26:27] offset:3072
	v_add_u32_e32 v5, 0xf000, v4
	global_load_dword v128, v5, s[26:27]
	global_load_dword v129, v5, s[26:27] offset:1024
	global_load_dword v130, v5, s[26:27] offset:2048
	global_load_dword v131, v5, s[26:27] offset:3072
	s_waitcnt vmcnt(0)
	v_add_f32_e32 v6, v6, v68
	v_add_f32_e32 v6, v6, v69
	v_add_f32_e32 v6, v6, v70
	v_add_f32_e32 v6, v6, v71
	v_add_f32_e32 v6, v6, v72
	v_add_f32_e32 v6, v6, v73
	v_add_f32_e32 v6, v6, v74
	v_add_f32_e32 v6, v6, v75
	v_add_f32_e32 v6, v6, v76
	v_add_f32_e32 v6, v6, v77
	v_add_f32_e32 v6, v6, v78
	v_add_f32_e32 v6, v6, v79
	v_add_f32_e32 v6, v6, v80
	v_add_f32_e32 v6, v6, v81
	v_add_f32_e32 v6, v6, v82
	v_add_f32_e32 v6, v6, v83
	v_add_f32_e32 v6, v6, v84
	v_add_f32_e32 v6, v6, v85
	v_add_f32_e32 v6, v6, v86
	v_add_f32_e32 v6, v6, v87
	v_add_f32_e32 v6, v6, v88
	v_add_f32_e32 v6, v6, v89
	v_add_f32_e32 v6, v6, v90
	v_add_f32_e32 v6, v6, v91
	v_add_f32_e32 v6, v6, v92
	v_add_f32_e32 v6, v6, v93
	v_add_f32_e32 v6, v6, v94
	v_add_f32_e32 v6, v6, v95
	v_add_f32_e32 v6, v6, v96
	v_add_f32_e32 v6, v6, v97
	v_add_f32_e32 v6, v6, v98
	v_add_f32_e32 v6, v6, v99
	v_add_f32_e32 v6, v6, v100
	v_add_f32_e32 v6, v6, v101
	v_add_f32_e32 v6, v6, v102
	v_add_f32_e32 v6, v6, v103
	v_add_f32_e32 v6, v6, v104
	v_add_f32_e32 v6, v6, v105
	v_add_f32_e32 v6, v6, v106
	v_add_f32_e32 v6, v6, v107
	v_add_f32_e32 v6, v6, v108
	v_add_f32_e32 v6, v6, v109
	v_add_f32_e32 v6, v6, v110
	v_add_f32_e32 v6, v6, v111
	v_add_f32_e32 v6, v6, v112
	v_add_f32_e32 v6, v6, v113
	v_add_f32_e32 v6, v6, v114
	v_add_f32_e32 v6, v6, v115
	v_add_f32_e32 v6, v6, v116
	v_add_f32_e32 v6, v6, v117
	v_add_f32_e32 v6, v6, v118
	v_add_f32_e32 v6, v6, v119
	v_add_f32_e32 v6, v6, v120
	v_add_f32_e32 v6, v6, v121
	v_add_f32_e32 v6, v6, v122
	v_add_f32_e32 v6, v6, v123
	v_add_f32_e32 v6, v6, v124
	v_add_f32_e32 v6, v6, v125
	v_add_f32_e32 v6, v6, v126
	v_add_f32_e32 v6, v6, v127
	v_add_f32_e32 v6, v6, v128
	v_add_f32_e32 v6, v6, v129
	v_add_f32_e32 v6, v6, v130
	v_add_f32_e32 v6, v6, v131
	v_readlane_b32 s2, v251, 53
	v_ashrrev_i32_e32 v3, 31, v2
	v_readlane_b32 s3, v251, 54
	s_nop 1
	v_lshl_add_u64 v[4:5], v[2:3], 2, s[2:3]
	global_store_dword v[4:5], v6, off

; DI float bf2f(bf16_t h) { return __uint_as_float(((unsigned)h) << 16); }
; DI void post_z(const Params& p, int layer) {
;     ...
;       int colbase; const float* g; float sc;
;       if (slab < 8) { colbase = C_Q + slab * 64; g = qn; sc = 0.125f; }
;       else if (slab < 10) { colbase = C_KS + (slab - 8) * 64; g = kn; sc = 1.f; }
;       else { colbase = C_KW + (slab - 10) * 64; g = kn; sc = 1.f; }
;       const float gv = g[lane] * sc;
;       float v[32];
; #pragma unroll
;       for (int i = 0; i < 32; ++i) v[i] = bf2f(zr[(size_t)i * ZS + colbase + lane]);
.LBB0_210:
	s_or_saveexec_b64 s[2:3], s[2:3]
	v_mov_b32_e32 v10, 1.0
	v_mov_b64_e32 v[8:9], s[10:11]
	s_xor_b64 exec, exec, s[2:3]
	v_lshlrev_b32_e32 v4, 6, v2
	v_mov_b32_e32 v10, 0x3e000000
	v_mov_b64_e32 v[8:9], s[40:41]
	s_or_b64 exec, exec, s[2:3]
	v_lshlrev_b32_e32 v0, 2, v32
	v_lshl_add_u64 v[2:3], v[8:9], 0, v[0:1]
	v_ashrrev_i32_e32 v5, 31, v4
	global_load_dword v11, v[2:3], off
	v_lshl_add_u64 v[2:3], v[4:5], 1, v[6:7]
	v_lshlrev_b32_e32 v0, 1, v32
	v_lshl_add_u64 v[78:79], v[2:3], 0, v[0:1]
	s_mov_b32 s98, 0x2a30
	s_mov_b32 s99, 0
	s_mov_b32 s12, 0x3c800000
	v_mov_b64_e32 v[116:117], v[78:79]
	v_mov_b64_e32 v[118:119], v[78:79]
	s_cmp_eq_u32 s90, 0
	s_cbranch_scc1 .Lnorm_ld
	s_waitcnt vmcnt(33)
	v_mov_b32_e32 v127, v80
	v_mov_b32_e32 v128, v81
	v_mov_b32_e32 v129, v82
	v_mov_b32_e32 v130, v83
	v_mov_b32_e32 v131, v84
	v_mov_b32_e32 v132, v85
	v_mov_b32_e32 v133, v86
	v_mov_b32_e32 v134, v87
	v_mov_b32_e32 v135, v88
	v_mov_b32_e32 v136, v89
	v_mov_b32_e32 v137, v90
	v_mov_b32_e32 v138, v91
	v_mov_b32_e32 v139, v92
	v_mov_b32_e32 v140, v93
	v_mov_b32_e32 v141, v94
	v_mov_b32_e32 v142, v95
	v_mov_b32_e32 v143, v96
	v_mov_b32_e32 v144, v97
	v_mov_b32_e32 v145, v98
	v_mov_b32_e32 v146, v99
	v_mov_b32_e32 v147, v100
	v_mov_b32_e32 v148, v101
	v_mov_b32_e32 v149, v102
	v_mov_b32_e32 v150, v103
	v_mov_b32_e32 v151, v104
	v_mov_b32_e32 v152, v105
	v_mov_b32_e32 v153, v106
	v_mov_b32_e32 v154, v107
	v_mov_b32_e32 v155, v108
	v_mov_b32_e32 v156, v109
	v_mov_b32_e32 v157, v110
	v_mov_b32_e32 v158, v111
	s_branch .Lnorm_hv
.Lnorm_ld:
	global_load_ushort v127, v[116:117], off
	v_lshl_add_u64 v[116:117], v[116:117], 0, s[98:99]
	global_load_ushort v128, v[116:117], off
	v_lshl_add_u64 v[116:117], v[116:117], 0, s[98:99]
	global_load_ushort v129, v[116:117], off
	v_lshl_add_u64 v[116:117], v[116:117], 0, s[98:99]
	global_load_ushort v130, v[116:117], off
	v_lshl_add_u64 v[116:117], v[116:117], 0, s[98:99]
	global_load_ushort v131, v[116:117], off
	v_lshl_add_u64 v[116:117], v[116:117], 0, s[98:99]
	global_load_ushort v132, v[116:117], off
	v_lshl_add_u64 v[116:117], v[116:117], 0, s[98:99]
	global_load_ushort v133, v[116:117], off
	v_lshl_add_u64 v[116:117], v[116:117], 0, s[98:99]
	global_load_ushort v134, v[116:117], off
	v_lshl_add_u64 v[116:117], v[116:117], 0, s[98:99]
	global_load_ushort v135, v[116:117], off
	v_lshl_add_u64 v[116:117], v[116:117], 0, s[98:99]
	global_load_ushort v136, v[116:117], off
	v_lshl_add_u64 v[116:117], v[116:117], 0, s[98:99]
	global_load_ushort v137, v[116:117], off
	v_lshl_add_u64 v[116:117], v[116:117], 0, s[98:99]
	global_load_ushort v138, v[116:117], off
	v_lshl_add_u64 v[116:117], v[116:117], 0, s[98:99]
	global_load_ushort v139, v[116:117], off
	v_lshl_add_u64 v[116:117], v[116:117], 0, s[98:99]
	global_load_ushort v140, v[116:117], off
	v_lshl_add_u64 v[116:117], v[116:117], 0, s[98:99]
	global_load_ushort v141, v[116:117], off
	v_lshl_add_u64 v[116:117], v[116:117], 0, s[98:99]
	global_load_ushort v142, v[116:117], off
	v_lshl_add_u64 v[116:117], v[116:117], 0, s[98:99]
	global_load_ushort v143, v[116:117], off
	v_lshl_add_u64 v[116:117], v[116:117], 0, s[98:99]
	global_load_ushort v144, v[116:117], off
	v_lshl_add_u64 v[116:117], v[116:117], 0, s[98:99]
	global_load_ushort v145, v[116:117], off
	v_lshl_add_u64 v[116:117], v[116:117], 0, s[98:99]
	global_load_ushort v146, v[116:117], off
	v_lshl_add_u64 v[116:117], v[116:117], 0, s[98:99]
	global_load_ushort v147, v[116:117], off
	v_lshl_add_u64 v[116:117], v[116:117], 0, s[98:99]
	global_load_ushort v148, v[116:117], off
	v_lshl_add_u64 v[116:117], v[116:117], 0, s[98:99]
	global_load_ushort v149, v[116:117], off
	v_lshl_add_u64 v[116:117], v[116:117], 0, s[98:99]
	global_load_ushort v150, v[116:117], off
	v_lshl_add_u64 v[116:117], v[116:117], 0, s[98:99]
	global_load_ushort v151, v[116:117], off
	v_lshl_add_u64 v[116:117], v[116:117], 0, s[98:99]
	global_load_ushort v152, v[116:117], off
	v_lshl_add_u64 v[116:117], v[116:117], 0, s[98:99]
	global_load_ushort v153, v[116:117], off
	v_lshl_add_u64 v[116:117], v[116:117], 0, s[98:99]
	global_load_ushort v154, v[116:117], off
	v_lshl_add_u64 v[116:117], v[116:117], 0, s[98:99]
	global_load_ushort v155, v[116:117], off
	v_lshl_add_u64 v[116:117], v[116:117], 0, s[98:99]
	global_load_ushort v156, v[116:117], off
	v_lshl_add_u64 v[116:117], v[116:117], 0, s[98:99]
	global_load_ushort v157, v[116:117], off
	v_lshl_add_u64 v[116:117], v[116:117], 0, s[98:99]
	global_load_ushort v158, v[116:117], off
	v_lshl_add_u64 v[116:117], v[116:117], 0, s[98:99]
; DI void post_z(const Params& p, int layer) {
;     ...
;   for (int item = gw; item < 1024 * 36; item += nw) {
;     const int tc = item / 36, slab = item - tc * 36;
;     const int tok0 = tc * 32;
;     const int b = tok0 >> 13, spos = tok0 & 8191;
;     bf16_t* zr = z + (size_t)tok0 * ZS;
;     if (slab >= 32) {
;       const int s4 = slab - 32, kv = s4 >> 1, gi = s4 & 1;
;       const int colbase = (kv ? C_VC : C_KC) + gi * 64;
;       bf16_t* dst = (bf16_t*)(p.ws + O_KVD) + ((size_t)((kv * 8 + b * 2 + gi) * SEQ + spos)) * 64 + lane;
;       bf16_t u[32];
; #pragma unroll
;       for (int i = 0; i < 32; ++i) u[i] = zr[(size_t)i * ZS + colbase + lane];
; #pragma unroll
;       for (int i = 0; i < 32; ++i) dst[i * 64] = u[i];
;     } else if (slab < 12) {
;       int colbase; const float* g; float sc;
;       if (slab < 8) { colbase = C_Q + slab * 64; g = qn; sc = 0.125f; }
;       else if (slab < 10) { colbase = C_KS + (slab - 8) * 64; g = kn; sc = 1.f; }
;       else { colbase = C_KW + (slab - 10) * 64; g = kn; sc = 1.f; }
;       const float gv = g[lane] * sc;
.Lnorm_hv:
	v_readfirstlane_b32 s84, v30
	s_mov_b32 s91, 0
	s_add_i32 s84, s84, s24
	s_cmp_lt_i32 s84, 0x9000
	s_cbranch_scc0 .Lnorm_np
	s_mul_hi_u32 s85, s84, 0x38e38e39
	s_lshr_b32 s85, s85, 3
	s_mul_i32 s86, s85, 36
	s_sub_i32 s86, s84, s86
	s_cmp_lt_u32 s86, 12
	s_cbranch_scc0 .Lnorm_np
	s_lshl_b32 s87, s86, 6
	s_add_i32 s88, s87, 0x100
	s_cmp_gt_u32 s86, 7
	s_cselect_b32 s87, s88, s87
	s_add_i32 s88, s88, 0x80
	s_cmp_gt_u32 s86, 9
	s_cselect_b32 s87, s88, s87
	s_mul_i32 s85, s85, 0x54600
	s_lshl_b32 s87, s87, 1
	s_add_u32 s85, s85, s87
	s_add_u32 s88, s16, s85
	s_addc_u32 s89, s17, 0
	v_lshlrev_b32_e32 v112, 1, v32
	v_mov_b32_e32 v113, 0
	v_lshl_add_u64 v[112:113], s[88:89], 0, v[112:113]
	global_load_ushort v80, v[112:113], off
	v_lshl_add_u64 v[112:113], v[112:113], 0, s[98:99]
	global_load_ushort v81, v[112:113], off
	v_lshl_add_u64 v[112:113], v[112:113], 0, s[98:99]
	global_load_ushort v82, v[112:113], off
	v_lshl_add_u64 v[112:113], v[112:113], 0, s[98:99]
	global_load_ushort v83, v[112:113], off
	v_lshl_add_u64 v[112:113], v[112:113], 0, s[98:99]
	global_load_ushort v84, v[112:113], off
	v_lshl_add_u64 v[112:113], v[112:113], 0, s[98:99]
	global_load_ushort v85, v[112:113], off
	v_lshl_add_u64 v[112:113], v[112:113], 0, s[98:99]
	global_load_ushort v86, v[112:113], off
	v_lshl_add_u64 v[112:113], v[112:113], 0, s[98:99]
	global_load_ushort v87, v[112:113], off
	v_lshl_add_u64 v[112:113], v[112:113], 0, s[98:99]
	global_load_ushort v88, v[112:113], off
	v_lshl_add_u64 v[112:113], v[112:113], 0, s[98:99]
	global_load_ushort v89, v[112:113], off
	v_lshl_add_u64 v[112:113], v[112:113], 0, s[98:99]
	global_load_ushort v90, v[112:113], off
	v_lshl_add_u64 v[112:113], v[112:113], 0, s[98:99]
	global_load_ushort v91, v[112:113], off
	v_lshl_add_u64 v[112:113], v[112:113], 0, s[98:99]
	global_load_ushort v92, v[112:113], off
	v_lshl_add_u64 v[112:113], v[112:113], 0, s[98:99]
	global_load_ushort v93, v[112:113], off
	v_lshl_add_u64 v[112:113], v[112:113], 0, s[98:99]
	global_load_ushort v94, v[112:113], off
	v_lshl_add_u64 v[112:113], v[112:113], 0, s[98:99]
	global_load_ushort v95, v[112:113], off
	v_lshl_add_u64 v[112:113], v[112:113], 0, s[98:99]
	global_load_ushort v96, v[112:113], off
	v_lshl_add_u64 v[112:113], v[112:113], 0, s[98:99]
	global_load_ushort v97, v[112:113], off
	v_lshl_add_u64 v[112:113], v[112:113], 0, s[98:99]
	global_load_ushort v98, v[112:113], off
	v_lshl_add_u64 v[112:113], v[112:113], 0, s[98:99]
	global_load_ushort v99, v[112:113], off
	v_lshl_add_u64 v[112:113], v[112:113], 0, s[98:99]
	global_load_ushort v100, v[112:113], off
	v_lshl_add_u64 v[112:113], v[112:113], 0, s[98:99]
	global_load_ushort v101, v[112:113], off
	v_lshl_add_u64 v[112:113], v[112:113], 0, s[98:99]
	global_load_ushort v102, v[112:113], off
	v_lshl_add_u64 v[112:113], v[112:113], 0, s[98:99]
	global_load_ushort v103, v[112:113], off
	v_lshl_add_u64 v[112:113], v[112:113], 0, s[98:99]
	global_load_ushort v104, v[112:113], off
	v_lshl_add_u64 v[112:113], v[112:113], 0, s[98:99]
	global_load_ushort v105, v[112:113], off
	v_lshl_add_u64 v[112:113], v[112:113], 0, s[98:99]
	global_load_ushort v106, v[112:113], off
	v_lshl_add_u64 v[112:113], v[112:113], 0, s[98:99]
	global_load_ushort v107, v[112:113], off
	v_lshl_add_u64 v[112:113], v[112:113], 0, s[98:99]
	global_load_ushort v108, v[112:113], off
	v_lshl_add_u64 v[112:113], v[112:113], 0, s[98:99]
	global_load_ushort v109, v[112:113], off
	v_lshl_add_u64 v[112:113], v[112:113], 0, s[98:99]
	global_load_ushort v110, v[112:113], off
	v_lshl_add_u64 v[112:113], v[112:113], 0, s[98:99]
	global_load_ushort v111, v[112:113], off
	v_lshl_add_u64 v[112:113], v[112:113], 0, s[98:99]
	s_mov_b32 s91, 1
.Lnorm_np:
	s_mov_b32 s90, s91
	v_mov_b32_e32 v121, 0x358637bd
	s_cmp_eq_u32 s91, 0
	s_cbranch_scc1 .Lnorm_w0
	s_waitcnt vmcnt(32)
	s_branch .Lnorm_go

; DI float bf2f(bf16_t h) { return __uint_as_float(((unsigned)h) << 16); }
; DI void post_z(const Params& p, int layer) {
;     ...
;       const float gv = g[lane] * sc;
;       float v[32];
; #pragma unroll
;       for (int i = 0; i < 32; ++i) v[i] = bf2f(zr[(size_t)i * ZS + colbase + lane]);
; #pragma unroll
;       for (int i = 0; i < 32; ++i) {
;         float ss = wave_sum(v[i] * v[i], lane);
.Lnorm_go:
	v_mul_f32_e32 v122, v10, v11
	v_lshlrev_b32_e32 v127, 16, v127
	v_lshlrev_b32_e32 v128, 16, v128
	v_lshlrev_b32_e32 v129, 16, v129
	v_lshlrev_b32_e32 v130, 16, v130
	v_lshlrev_b32_e32 v131, 16, v131
	v_lshlrev_b32_e32 v132, 16, v132
	v_lshlrev_b32_e32 v133, 16, v133
	v_lshlrev_b32_e32 v134, 16, v134
	v_lshlrev_b32_e32 v135, 16, v135
	v_lshlrev_b32_e32 v136, 16, v136
	v_lshlrev_b32_e32 v137, 16, v137
	v_lshlrev_b32_e32 v138, 16, v138
	v_lshlrev_b32_e32 v139, 16, v139
	v_lshlrev_b32_e32 v140, 16, v140
	v_lshlrev_b32_e32 v141, 16, v141
	v_lshlrev_b32_e32 v142, 16, v142
	v_lshlrev_b32_e32 v143, 16, v143
	v_lshlrev_b32_e32 v144, 16, v144
	v_lshlrev_b32_e32 v145, 16, v145
	v_lshlrev_b32_e32 v146, 16, v146
	v_lshlrev_b32_e32 v147, 16, v147
	v_lshlrev_b32_e32 v148, 16, v148
	v_lshlrev_b32_e32 v149, 16, v149
	v_lshlrev_b32_e32 v150, 16, v150
	v_lshlrev_b32_e32 v151, 16, v151
	v_lshlrev_b32_e32 v152, 16, v152
	v_lshlrev_b32_e32 v153, 16, v153
	v_lshlrev_b32_e32 v154, 16, v154
	v_lshlrev_b32_e32 v155, 16, v155
	v_lshlrev_b32_e32 v156, 16, v156
	v_lshlrev_b32_e32 v157, 16, v157
	v_lshlrev_b32_e32 v158, 16, v158
	v_mul_f32_e32 v215, v127, v127
	v_mul_f32_e32 v216, v128, v128
	v_mul_f32_e32 v217, v129, v129
	v_mul_f32_e32 v218, v130, v130
	v_mul_f32_e32 v219, v131, v131
	v_mul_f32_e32 v220, v132, v132
	v_mul_f32_e32 v221, v133, v133
	v_mul_f32_e32 v222, v134, v134
	v_mul_f32_e32 v223, v135, v135
	v_mul_f32_e32 v224, v136, v136
	v_mul_f32_e32 v225, v137, v137
	v_mul_f32_e32 v226, v138, v138
	v_mul_f32_e32 v227, v139, v139
	v_mul_f32_e32 v228, v140, v140
	v_mul_f32_e32 v229, v141, v141
	v_mul_f32_e32 v230, v142, v142
	v_mul_f32_e32 v231, v143, v143
	v_mul_f32_e32 v232, v144, v144
	v_mul_f32_e32 v233, v145, v145
	v_mul_f32_e32 v234, v146, v146
	v_mul_f32_e32 v235, v147, v147
	v_mul_f32_e32 v236, v148, v148
	v_mul_f32_e32 v237, v149, v149
	v_mul_f32_e32 v238, v150, v150
	v_mul_f32_e32 v239, v151, v151
	v_mul_f32_e32 v240, v152, v152
	v_mul_f32_e32 v241, v153, v153
	v_mul_f32_e32 v242, v154, v154
	v_mul_f32_e32 v243, v155, v155
	v_mul_f32_e32 v244, v156, v156
	v_mul_f32_e32 v245, v157, v157
	v_mul_f32_e32 v246, v158, v158
	v_add_f32_dpp v215, v215, v215 quad_perm:[1,0,3,2] row_mask:0xf bank_mask:0xf
	v_add_f32_dpp v216, v216, v216 quad_perm:[1,0,3,2] row_mask:0xf bank_mask:0xf
	v_add_f32_dpp v217, v217, v217 quad_perm:[1,0,3,2] row_mask:0xf bank_mask:0xf
	v_add_f32_dpp v218, v218, v218 quad_perm:[1,0,3,2] row_mask:0xf bank_mask:0xf
	v_add_f32_dpp v219, v219, v219 quad_perm:[1,0,3,2] row_mask:0xf bank_mask:0xf
	v_add_f32_dpp v220, v220, v220 quad_perm:[1,0,3,2] row_mask:0xf bank_mask:0xf
	v_add_f32_dpp v221, v221, v221 quad_perm:[1,0,3,2] row_mask:0xf bank_mask:0xf
	v_add_f32_dpp v222, v222, v222 quad_perm:[1,0,3,2] row_mask:0xf bank_mask:0xf
	v_add_f32_dpp v223, v223, v223 quad_perm:[1,0,3,2] row_mask:0xf bank_mask:0xf
	v_add_f32_dpp v224, v224, v224 quad_perm:[1,0,3,2] row_mask:0xf bank_mask:0xf
	v_add_f32_dpp v225, v225, v225 quad_perm:[1,0,3,2] row_mask:0xf bank_mask:0xf
	v_add_f32_dpp v226, v226, v226 quad_perm:[1,0,3,2] row_mask:0xf bank_mask:0xf
	v_add_f32_dpp v227, v227, v227 quad_perm:[1,0,3,2] row_mask:0xf bank_mask:0xf
	v_add_f32_dpp v228, v228, v228 quad_perm:[1,0,3,2] row_mask:0xf bank_mask:0xf
	v_add_f32_dpp v229, v229, v229 quad_perm:[1,0,3,2] row_mask:0xf bank_mask:0xf
	v_add_f32_dpp v230, v230, v230 quad_perm:[1,0,3,2] row_mask:0xf bank_mask:0xf
	v_add_f32_dpp v231, v231, v231 quad_perm:[1,0,3,2] row_mask:0xf bank_mask:0xf
	v_add_f32_dpp v232, v232, v232 quad_perm:[1,0,3,2] row_mask:0xf bank_mask:0xf
	v_add_f32_dpp v233, v233, v233 quad_perm:[1,0,3,2] row_mask:0xf bank_mask:0xf
	v_add_f32_dpp v234, v234, v234 quad_perm:[1,0,3,2] row_mask:0xf bank_mask:0xf
	v_add_f32_dpp v235, v235, v235 quad_perm:[1,0,3,2] row_mask:0xf bank_mask:0xf
	v_add_f32_dpp v236, v236, v236 quad_perm:[1,0,3,2] row_mask:0xf bank_mask:0xf
	v_add_f32_dpp v237, v237, v237 quad_perm:[1,0,3,2] row_mask:0xf bank_mask:0xf
	v_add_f32_dpp v238, v238, v238 quad_perm:[1,0,3,2] row_mask:0xf bank_mask:0xf
	v_add_f32_dpp v239, v239, v239 quad_perm:[1,0,3,2] row_mask:0xf bank_mask:0xf
	v_add_f32_dpp v240, v240, v240 quad_perm:[1,0,3,2] row_mask:0xf bank_mask:0xf
	v_add_f32_dpp v241, v241, v241 quad_perm:[1,0,3,2] row_mask:0xf bank_mask:0xf
	v_add_f32_dpp v242, v242, v242 quad_perm:[1,0,3,2] row_mask:0xf bank_mask:0xf
	v_add_f32_dpp v243, v243, v243 quad_perm:[1,0,3,2] row_mask:0xf bank_mask:0xf
	v_add_f32_dpp v244, v244, v244 quad_perm:[1,0,3,2] row_mask:0xf bank_mask:0xf
	v_add_f32_dpp v245, v245, v245 quad_perm:[1,0,3,2] row_mask:0xf bank_mask:0xf
	v_add_f32_dpp v246, v246, v246 quad_perm:[1,0,3,2] row_mask:0xf bank_mask:0xf
	v_add_f32_dpp v215, v215, v215 quad_perm:[2,3,0,1] row_mask:0xf bank_mask:0xf
	v_add_f32_dpp v216, v216, v216 quad_perm:[2,3,0,1] row_mask:0xf bank_mask:0xf
	v_add_f32_dpp v217, v217, v217 quad_perm:[2,3,0,1] row_mask:0xf bank_mask:0xf
	v_add_f32_dpp v218, v218, v218 quad_perm:[2,3,0,1] row_mask:0xf bank_mask:0xf
	v_add_f32_dpp v219, v219, v219 quad_perm:[2,3,0,1] row_mask:0xf bank_mask:0xf
	v_add_f32_dpp v220, v220, v220 quad_perm:[2,3,0,1] row_mask:0xf bank_mask:0xf
	v_add_f32_dpp v221, v221, v221 quad_perm:[2,3,0,1] row_mask:0xf bank_mask:0xf
	v_add_f32_dpp v222, v222, v222 quad_perm:[2,3,0,1] row_mask:0xf bank_mask:0xf
	v_add_f32_dpp v223, v223, v223 quad_perm:[2,3,0,1] row_mask:0xf bank_mask:0xf
	v_add_f32_dpp v224, v224, v224 quad_perm:[2,3,0,1] row_mask:0xf bank_mask:0xf
	v_add_f32_dpp v225, v225, v225 quad_perm:[2,3,0,1] row_mask:0xf bank_mask:0xf
	v_add_f32_dpp v226, v226, v226 quad_perm:[2,3,0,1] row_mask:0xf bank_mask:0xf
; DI void post_z(const Params& p, int layer) {
;     ...
;         float ss = wave_sum(v[i] * v[i], lane);
	v_add_f32_dpp v227, v227, v227 quad_perm:[2,3,0,1] row_mask:0xf bank_mask:0xf
	v_add_f32_dpp v228, v228, v228 quad_perm:[2,3,0,1] row_mask:0xf bank_mask:0xf
	v_add_f32_dpp v229, v229, v229 quad_perm:[2,3,0,1] row_mask:0xf bank_mask:0xf
	v_add_f32_dpp v230, v230, v230 quad_perm:[2,3,0,1] row_mask:0xf bank_mask:0xf
	v_add_f32_dpp v231, v231, v231 quad_perm:[2,3,0,1] row_mask:0xf bank_mask:0xf
	v_add_f32_dpp v232, v232, v232 quad_perm:[2,3,0,1] row_mask:0xf bank_mask:0xf
	v_add_f32_dpp v233, v233, v233 quad_perm:[2,3,0,1] row_mask:0xf bank_mask:0xf
	v_add_f32_dpp v234, v234, v234 quad_perm:[2,3,0,1] row_mask:0xf bank_mask:0xf
	v_add_f32_dpp v235, v235, v235 quad_perm:[2,3,0,1] row_mask:0xf bank_mask:0xf
	v_add_f32_dpp v236, v236, v236 quad_perm:[2,3,0,1] row_mask:0xf bank_mask:0xf
	v_add_f32_dpp v237, v237, v237 quad_perm:[2,3,0,1] row_mask:0xf bank_mask:0xf
	v_add_f32_dpp v238, v238, v238 quad_perm:[2,3,0,1] row_mask:0xf bank_mask:0xf
	v_add_f32_dpp v239, v239, v239 quad_perm:[2,3,0,1] row_mask:0xf bank_mask:0xf
	v_add_f32_dpp v240, v240, v240 quad_perm:[2,3,0,1] row_mask:0xf bank_mask:0xf
	v_add_f32_dpp v241, v241, v241 quad_perm:[2,3,0,1] row_mask:0xf bank_mask:0xf
	v_add_f32_dpp v242, v242, v242 quad_perm:[2,3,0,1] row_mask:0xf bank_mask:0xf
	v_add_f32_dpp v243, v243, v243 quad_perm:[2,3,0,1] row_mask:0xf bank_mask:0xf
	v_add_f32_dpp v244, v244, v244 quad_perm:[2,3,0,1] row_mask:0xf bank_mask:0xf
	v_add_f32_dpp v245, v245, v245 quad_perm:[2,3,0,1] row_mask:0xf bank_mask:0xf
	v_add_f32_dpp v246, v246, v246 quad_perm:[2,3,0,1] row_mask:0xf bank_mask:0xf
	v_add_f32_dpp v215, v215, v215 row_half_mirror row_mask:0xf bank_mask:0xf
	v_add_f32_dpp v216, v216, v216 row_half_mirror row_mask:0xf bank_mask:0xf
	v_add_f32_dpp v217, v217, v217 row_half_mirror row_mask:0xf bank_mask:0xf
	v_add_f32_dpp v218, v218, v218 row_half_mirror row_mask:0xf bank_mask:0xf
	v_add_f32_dpp v219, v219, v219 row_half_mirror row_mask:0xf bank_mask:0xf
	v_add_f32_dpp v220, v220, v220 row_half_mirror row_mask:0xf bank_mask:0xf
	v_add_f32_dpp v221, v221, v221 row_half_mirror row_mask:0xf bank_mask:0xf
	v_add_f32_dpp v222, v222, v222 row_half_mirror row_mask:0xf bank_mask:0xf
	v_add_f32_dpp v223, v223, v223 row_half_mirror row_mask:0xf bank_mask:0xf
	v_add_f32_dpp v224, v224, v224 row_half_mirror row_mask:0xf bank_mask:0xf
	v_add_f32_dpp v225, v225, v225 row_half_mirror row_mask:0xf bank_mask:0xf
	v_add_f32_dpp v226, v226, v226 row_half_mirror row_mask:0xf bank_mask:0xf
	v_add_f32_dpp v227, v227, v227 row_half_mirror row_mask:0xf bank_mask:0xf
	v_add_f32_dpp v228, v228, v228 row_half_mirror row_mask:0xf bank_mask:0xf
	v_add_f32_dpp v229, v229, v229 row_half_mirror row_mask:0xf bank_mask:0xf
	v_add_f32_dpp v230, v230, v230 row_half_mirror row_mask:0xf bank_mask:0xf
	v_add_f32_dpp v231, v231, v231 row_half_mirror row_mask:0xf bank_mask:0xf
	v_add_f32_dpp v232, v232, v232 row_half_mirror row_mask:0xf bank_mask:0xf
	v_add_f32_dpp v233, v233, v233 row_half_mirror row_mask:0xf bank_mask:0xf
	v_add_f32_dpp v234, v234, v234 row_half_mirror row_mask:0xf bank_mask:0xf
	v_add_f32_dpp v235, v235, v235 row_half_mirror row_mask:0xf bank_mask:0xf
	v_add_f32_dpp v236, v236, v236 row_half_mirror row_mask:0xf bank_mask:0xf
	v_add_f32_dpp v237, v237, v237 row_half_mirror row_mask:0xf bank_mask:0xf
	v_add_f32_dpp v238, v238, v238 row_half_mirror row_mask:0xf bank_mask:0xf
	v_add_f32_dpp v239, v239, v239 row_half_mirror row_mask:0xf bank_mask:0xf
	v_add_f32_dpp v240, v240, v240 row_half_mirror row_mask:0xf bank_mask:0xf
	v_add_f32_dpp v241, v241, v241 row_half_mirror row_mask:0xf bank_mask:0xf
	v_add_f32_dpp v242, v242, v242 row_half_mirror row_mask:0xf bank_mask:0xf
	v_add_f32_dpp v243, v243, v243 row_half_mirror row_mask:0xf bank_mask:0xf
	v_add_f32_dpp v244, v244, v244 row_half_mirror row_mask:0xf bank_mask:0xf
	v_add_f32_dpp v245, v245, v245 row_half_mirror row_mask:0xf bank_mask:0xf
	v_add_f32_dpp v246, v246, v246 row_half_mirror row_mask:0xf bank_mask:0xf
	v_add_f32_dpp v215, v215, v215 row_mirror row_mask:0xf bank_mask:0xf
	v_add_f32_dpp v216, v216, v216 row_mirror row_mask:0xf bank_mask:0xf
	v_add_f32_dpp v217, v217, v217 row_mirror row_mask:0xf bank_mask:0xf
	v_add_f32_dpp v218, v218, v218 row_mirror row_mask:0xf bank_mask:0xf
	v_add_f32_dpp v219, v219, v219 row_mirror row_mask:0xf bank_mask:0xf
	v_add_f32_dpp v220, v220, v220 row_mirror row_mask:0xf bank_mask:0xf
	v_add_f32_dpp v221, v221, v221 row_mirror row_mask:0xf bank_mask:0xf
	v_add_f32_dpp v222, v222, v222 row_mirror row_mask:0xf bank_mask:0xf
	v_add_f32_dpp v223, v223, v223 row_mirror row_mask:0xf bank_mask:0xf
	v_add_f32_dpp v224, v224, v224 row_mirror row_mask:0xf bank_mask:0xf
	v_add_f32_dpp v225, v225, v225 row_mirror row_mask:0xf bank_mask:0xf
	v_add_f32_dpp v226, v226, v226 row_mirror row_mask:0xf bank_mask:0xf
	v_add_f32_dpp v227, v227, v227 row_mirror row_mask:0xf bank_mask:0xf
	v_add_f32_dpp v228, v228, v228 row_mirror row_mask:0xf bank_mask:0xf
	v_add_f32_dpp v229, v229, v229 row_mirror row_mask:0xf bank_mask:0xf
	v_add_f32_dpp v230, v230, v230 row_mirror row_mask:0xf bank_mask:0xf
	v_add_f32_dpp v231, v231, v231 row_mirror row_mask:0xf bank_mask:0xf
	v_add_f32_dpp v232, v232, v232 row_mirror row_mask:0xf bank_mask:0xf
	v_add_f32_dpp v233, v233, v233 row_mirror row_mask:0xf bank_mask:0xf
	v_add_f32_dpp v234, v234, v234 row_mirror row_mask:0xf bank_mask:0xf
	v_add_f32_dpp v235, v235, v235 row_mirror row_mask:0xf bank_mask:0xf
	v_add_f32_dpp v236, v236, v236 row_mirror row_mask:0xf bank_mask:0xf
	v_add_f32_dpp v237, v237, v237 row_mirror row_mask:0xf bank_mask:0xf
	v_add_f32_dpp v238, v238, v238 row_mirror row_mask:0xf bank_mask:0xf
; DI void post_z(const Params& p, int layer) {
;     ...
;         float ss = wave_sum(v[i] * v[i], lane);
	v_add_f32_dpp v239, v239, v239 row_mirror row_mask:0xf bank_mask:0xf
	v_add_f32_dpp v240, v240, v240 row_mirror row_mask:0xf bank_mask:0xf
	v_add_f32_dpp v241, v241, v241 row_mirror row_mask:0xf bank_mask:0xf
	v_add_f32_dpp v242, v242, v242 row_mirror row_mask:0xf bank_mask:0xf
	v_add_f32_dpp v243, v243, v243 row_mirror row_mask:0xf bank_mask:0xf
	v_add_f32_dpp v244, v244, v244 row_mirror row_mask:0xf bank_mask:0xf
	v_add_f32_dpp v245, v245, v245 row_mirror row_mask:0xf bank_mask:0xf
	v_add_f32_dpp v246, v246, v246 row_mirror row_mask:0xf bank_mask:0xf
	v_add_f32_dpp v215, v215, v215 row_bcast:15 row_mask:0xa bank_mask:0xf
	v_add_f32_dpp v216, v216, v216 row_bcast:15 row_mask:0xa bank_mask:0xf
	v_add_f32_dpp v217, v217, v217 row_bcast:15 row_mask:0xa bank_mask:0xf
	v_add_f32_dpp v218, v218, v218 row_bcast:15 row_mask:0xa bank_mask:0xf
	v_add_f32_dpp v219, v219, v219 row_bcast:15 row_mask:0xa bank_mask:0xf
	v_add_f32_dpp v220, v220, v220 row_bcast:15 row_mask:0xa bank_mask:0xf
	v_add_f32_dpp v221, v221, v221 row_bcast:15 row_mask:0xa bank_mask:0xf
	v_add_f32_dpp v222, v222, v222 row_bcast:15 row_mask:0xa bank_mask:0xf
	v_add_f32_dpp v223, v223, v223 row_bcast:15 row_mask:0xa bank_mask:0xf
	v_add_f32_dpp v224, v224, v224 row_bcast:15 row_mask:0xa bank_mask:0xf
	v_add_f32_dpp v225, v225, v225 row_bcast:15 row_mask:0xa bank_mask:0xf
	v_add_f32_dpp v226, v226, v226 row_bcast:15 row_mask:0xa bank_mask:0xf
	v_add_f32_dpp v227, v227, v227 row_bcast:15 row_mask:0xa bank_mask:0xf
	v_add_f32_dpp v228, v228, v228 row_bcast:15 row_mask:0xa bank_mask:0xf
	v_add_f32_dpp v229, v229, v229 row_bcast:15 row_mask:0xa bank_mask:0xf
	v_add_f32_dpp v230, v230, v230 row_bcast:15 row_mask:0xa bank_mask:0xf
	v_add_f32_dpp v231, v231, v231 row_bcast:15 row_mask:0xa bank_mask:0xf
	v_add_f32_dpp v232, v232, v232 row_bcast:15 row_mask:0xa bank_mask:0xf
	v_add_f32_dpp v233, v233, v233 row_bcast:15 row_mask:0xa bank_mask:0xf
	v_add_f32_dpp v234, v234, v234 row_bcast:15 row_mask:0xa bank_mask:0xf
	v_add_f32_dpp v235, v235, v235 row_bcast:15 row_mask:0xa bank_mask:0xf
	v_add_f32_dpp v236, v236, v236 row_bcast:15 row_mask:0xa bank_mask:0xf
	v_add_f32_dpp v237, v237, v237 row_bcast:15 row_mask:0xa bank_mask:0xf
	v_add_f32_dpp v238, v238, v238 row_bcast:15 row_mask:0xa bank_mask:0xf
	v_add_f32_dpp v239, v239, v239 row_bcast:15 row_mask:0xa bank_mask:0xf
	v_add_f32_dpp v240, v240, v240 row_bcast:15 row_mask:0xa bank_mask:0xf
	v_add_f32_dpp v241, v241, v241 row_bcast:15 row_mask:0xa bank_mask:0xf
	v_add_f32_dpp v242, v242, v242 row_bcast:15 row_mask:0xa bank_mask:0xf
	v_add_f32_dpp v243, v243, v243 row_bcast:15 row_mask:0xa bank_mask:0xf
	v_add_f32_dpp v244, v244, v244 row_bcast:15 row_mask:0xa bank_mask:0xf
	v_add_f32_dpp v245, v245, v245 row_bcast:15 row_mask:0xa bank_mask:0xf
	v_add_f32_dpp v246, v246, v246 row_bcast:15 row_mask:0xa bank_mask:0xf
	v_add_f32_dpp v215, v215, v215 row_bcast:31 row_mask:0xc bank_mask:0xf
	v_add_f32_dpp v216, v216, v216 row_bcast:31 row_mask:0xc bank_mask:0xf
	v_add_f32_dpp v217, v217, v217 row_bcast:31 row_mask:0xc bank_mask:0xf
	v_add_f32_dpp v218, v218, v218 row_bcast:31 row_mask:0xc bank_mask:0xf
	v_add_f32_dpp v219, v219, v219 row_bcast:31 row_mask:0xc bank_mask:0xf
	v_add_f32_dpp v220, v220, v220 row_bcast:31 row_mask:0xc bank_mask:0xf
	v_add_f32_dpp v221, v221, v221 row_bcast:31 row_mask:0xc bank_mask:0xf
	v_add_f32_dpp v222, v222, v222 row_bcast:31 row_mask:0xc bank_mask:0xf
	v_add_f32_dpp v223, v223, v223 row_bcast:31 row_mask:0xc bank_mask:0xf
	v_add_f32_dpp v224, v224, v224 row_bcast:31 row_mask:0xc bank_mask:0xf
	v_add_f32_dpp v225, v225, v225 row_bcast:31 row_mask:0xc bank_mask:0xf
	v_add_f32_dpp v226, v226, v226 row_bcast:31 row_mask:0xc bank_mask:0xf
	v_add_f32_dpp v227, v227, v227 row_bcast:31 row_mask:0xc bank_mask:0xf
	v_add_f32_dpp v228, v228, v228 row_bcast:31 row_mask:0xc bank_mask:0xf
	v_add_f32_dpp v229, v229, v229 row_bcast:31 row_mask:0xc bank_mask:0xf
	v_add_f32_dpp v230, v230, v230 row_bcast:31 row_mask:0xc bank_mask:0xf
	v_add_f32_dpp v231, v231, v231 row_bcast:31 row_mask:0xc bank_mask:0xf
	v_add_f32_dpp v232, v232, v232 row_bcast:31 row_mask:0xc bank_mask:0xf
	v_add_f32_dpp v233, v233, v233 row_bcast:31 row_mask:0xc bank_mask:0xf
	v_add_f32_dpp v234, v234, v234 row_bcast:31 row_mask:0xc bank_mask:0xf
	v_add_f32_dpp v235, v235, v235 row_bcast:31 row_mask:0xc bank_mask:0xf
	v_add_f32_dpp v236, v236, v236 row_bcast:31 row_mask:0xc bank_mask:0xf
	v_add_f32_dpp v237, v237, v237 row_bcast:31 row_mask:0xc bank_mask:0xf
	v_add_f32_dpp v238, v238, v238 row_bcast:31 row_mask:0xc bank_mask:0xf
	v_add_f32_dpp v239, v239, v239 row_bcast:31 row_mask:0xc bank_mask:0xf
	v_add_f32_dpp v240, v240, v240 row_bcast:31 row_mask:0xc bank_mask:0xf
	v_add_f32_dpp v241, v241, v241 row_bcast:31 row_mask:0xc bank_mask:0xf
	v_add_f32_dpp v242, v242, v242 row_bcast:31 row_mask:0xc bank_mask:0xf
	v_add_f32_dpp v243, v243, v243 row_bcast:31 row_mask:0xc bank_mask:0xf
	v_add_f32_dpp v244, v244, v244 row_bcast:31 row_mask:0xc bank_mask:0xf
	v_add_f32_dpp v245, v245, v245 row_bcast:31 row_mask:0xc bank_mask:0xf
	v_add_f32_dpp v246, v246, v246 row_bcast:31 row_mask:0xc bank_mask:0xf
	s_nop 1
	v_readlane_b32 s46, v215, 63
	v_readlane_b32 s47, v216, 63
	v_readlane_b32 s48, v217, 63
	v_readlane_b32 s49, v218, 63
	v_readlane_b32 s50, v219, 63
	v_readlane_b32 s51, v220, 63
	v_readlane_b32 s52, v221, 63
	v_readlane_b32 s53, v222, 63
	v_readlane_b32 s54, v223, 63
	v_readlane_b32 s55, v224, 63
	v_readlane_b32 s56, v225, 63
	v_readlane_b32 s57, v226, 63
	v_readlane_b32 s58, v227, 63
	v_readlane_b32 s59, v228, 63
	v_readlane_b32 s60, v229, 63
; DI bf16_t f2bf(float a) { return (bf16_t)(pack2(a, 0.f) & 0xffffu); }
; DI void post_z(const Params& p, int layer) {
;     ...
;         float ss = wave_sum(v[i] * v[i], lane);
;         float rs = rsqrtf(ss * (1.f / 64.f) + 1e-6f);
;         zr[(size_t)i * ZS + colbase + lane] = f2bf(v[i] * rs * gv);
	v_readlane_b32 s61, v230, 63
	v_readlane_b32 s62, v231, 63
	v_readlane_b32 s63, v232, 63
	v_readlane_b32 s64, v233, 63
	v_readlane_b32 s65, v234, 63
	v_readlane_b32 s66, v235, 63
	v_readlane_b32 s67, v236, 63
	v_readlane_b32 s68, v237, 63
	v_readlane_b32 s69, v238, 63
	v_readlane_b32 s70, v239, 63
	v_readlane_b32 s71, v240, 63
	v_readlane_b32 s72, v241, 63
	v_readlane_b32 s73, v242, 63
	v_readlane_b32 s74, v243, 63
	v_readlane_b32 s75, v244, 63
	v_readlane_b32 s76, v245, 63
	v_readlane_b32 s77, v246, 63
	v_mov_b32_e32 v215, s46
	v_mov_b32_e32 v216, s47
	v_mov_b32_e32 v217, s48
	v_mov_b32_e32 v218, s49
	v_mov_b32_e32 v219, s50
	v_mov_b32_e32 v220, s51
	v_mov_b32_e32 v221, s52
	v_mov_b32_e32 v222, s53
	v_mov_b32_e32 v223, s54
	v_mov_b32_e32 v224, s55
	v_mov_b32_e32 v225, s56
	v_mov_b32_e32 v226, s57
	v_mov_b32_e32 v227, s58
	v_mov_b32_e32 v228, s59
	v_mov_b32_e32 v229, s60
	v_mov_b32_e32 v230, s61
	v_mov_b32_e32 v231, s62
	v_mov_b32_e32 v232, s63
	v_mov_b32_e32 v233, s64
	v_mov_b32_e32 v234, s65
	v_mov_b32_e32 v235, s66
	v_mov_b32_e32 v236, s67
	v_mov_b32_e32 v237, s68
	v_mov_b32_e32 v238, s69
	v_mov_b32_e32 v239, s70
	v_mov_b32_e32 v240, s71
	v_mov_b32_e32 v241, s72
	v_mov_b32_e32 v242, s73
	v_mov_b32_e32 v243, s74
	v_mov_b32_e32 v244, s75
	v_mov_b32_e32 v245, s76
	v_mov_b32_e32 v246, s77
	v_fmamk_f32 v215, v215, 0x3c800000, v121
	v_fmamk_f32 v216, v216, 0x3c800000, v121
	v_fmamk_f32 v217, v217, 0x3c800000, v121
	v_fmamk_f32 v218, v218, 0x3c800000, v121
	v_fmamk_f32 v219, v219, 0x3c800000, v121
	v_fmamk_f32 v220, v220, 0x3c800000, v121
	v_fmamk_f32 v221, v221, 0x3c800000, v121
	v_fmamk_f32 v222, v222, 0x3c800000, v121
	v_fmamk_f32 v223, v223, 0x3c800000, v121
	v_fmamk_f32 v224, v224, 0x3c800000, v121
	v_fmamk_f32 v225, v225, 0x3c800000, v121
	v_fmamk_f32 v226, v226, 0x3c800000, v121
	v_fmamk_f32 v227, v227, 0x3c800000, v121
	v_fmamk_f32 v228, v228, 0x3c800000, v121
	v_fmamk_f32 v229, v229, 0x3c800000, v121
	v_fmamk_f32 v230, v230, 0x3c800000, v121
	v_fmamk_f32 v231, v231, 0x3c800000, v121
	v_fmamk_f32 v232, v232, 0x3c800000, v121
	v_fmamk_f32 v233, v233, 0x3c800000, v121
	v_fmamk_f32 v234, v234, 0x3c800000, v121
	v_fmamk_f32 v235, v235, 0x3c800000, v121
	v_fmamk_f32 v236, v236, 0x3c800000, v121
	v_fmamk_f32 v237, v237, 0x3c800000, v121
	v_fmamk_f32 v238, v238, 0x3c800000, v121
	v_fmamk_f32 v239, v239, 0x3c800000, v121
	v_fmamk_f32 v240, v240, 0x3c800000, v121
	v_fmamk_f32 v241, v241, 0x3c800000, v121
	v_fmamk_f32 v242, v242, 0x3c800000, v121
	v_fmamk_f32 v243, v243, 0x3c800000, v121
	v_fmamk_f32 v244, v244, 0x3c800000, v121
	v_fmamk_f32 v245, v245, 0x3c800000, v121
	v_fmamk_f32 v246, v246, 0x3c800000, v121
	v_rsq_f32_e32 v215, v215
	v_rsq_f32_e32 v216, v216
	v_rsq_f32_e32 v217, v217
	v_rsq_f32_e32 v218, v218
	v_rsq_f32_e32 v219, v219
	v_rsq_f32_e32 v220, v220
	v_rsq_f32_e32 v221, v221
	v_rsq_f32_e32 v222, v222
	v_rsq_f32_e32 v223, v223
	v_rsq_f32_e32 v224, v224
	v_rsq_f32_e32 v225, v225
	v_rsq_f32_e32 v226, v226
	v_rsq_f32_e32 v227, v227
	v_rsq_f32_e32 v228, v228
	v_rsq_f32_e32 v229, v229
	v_rsq_f32_e32 v230, v230
	v_rsq_f32_e32 v231, v231
	v_rsq_f32_e32 v232, v232
	v_rsq_f32_e32 v233, v233
	v_rsq_f32_e32 v234, v234
	v_rsq_f32_e32 v235, v235
	v_rsq_f32_e32 v236, v236
	v_rsq_f32_e32 v237, v237
	v_rsq_f32_e32 v238, v238
	v_rsq_f32_e32 v239, v239
	v_rsq_f32_e32 v240, v240
	v_rsq_f32_e32 v241, v241
	v_rsq_f32_e32 v242, v242
	v_rsq_f32_e32 v243, v243
	v_rsq_f32_e32 v244, v244
	v_rsq_f32_e32 v245, v245
	v_rsq_f32_e32 v246, v246
	v_mul_f32_e32 v127, v215, v127
	v_mul_f32_e32 v128, v216, v128
	v_mul_f32_e32 v129, v217, v129
	v_mul_f32_e32 v130, v218, v130
	v_mul_f32_e32 v131, v219, v131
	v_mul_f32_e32 v132, v220, v132
	v_mul_f32_e32 v133, v221, v133
	v_mul_f32_e32 v134, v222, v134
	v_mul_f32_e32 v135, v223, v135
	v_mul_f32_e32 v136, v224, v136
	v_mul_f32_e32 v137, v225, v137
	v_mul_f32_e32 v138, v226, v138
	v_mul_f32_e32 v139, v227, v139
	v_mul_f32_e32 v140, v228, v140
	v_mul_f32_e32 v141, v229, v141
	v_mul_f32_e32 v142, v230, v142
	v_mul_f32_e32 v143, v231, v143
	v_mul_f32_e32 v144, v232, v144
	v_mul_f32_e32 v145, v233, v145
	v_mul_f32_e32 v146, v234, v146
	v_mul_f32_e32 v147, v235, v147
	v_mul_f32_e32 v148, v236, v148
	v_mul_f32_e32 v149, v237, v149
	v_mul_f32_e32 v150, v238, v150
	v_mul_f32_e32 v151, v239, v151
	v_mul_f32_e32 v152, v240, v152
	v_mul_f32_e32 v153, v241, v153
	v_mul_f32_e32 v154, v242, v154
	v_mul_f32_e32 v155, v243, v155
	v_mul_f32_e32 v156, v244, v156
	v_mul_f32_e32 v157, v245, v157
	v_mul_f32_e32 v158, v246, v158
	v_mul_f32_e32 v127, v122, v127
	v_mul_f32_e32 v128, v122, v128
	v_mul_f32_e32 v129, v122, v129
	v_mul_f32_e32 v130, v122, v130
	v_mul_f32_e32 v131, v122, v131
	v_mul_f32_e32 v132, v122, v132
	v_mul_f32_e32 v133, v122, v133
	v_mul_f32_e32 v134, v122, v134
	v_mul_f32_e32 v135, v122, v135
	v_mul_f32_e32 v136, v122, v136
; DI bf16_t f2bf(float a) { return (bf16_t)(pack2(a, 0.f) & 0xffffu); }
; DI void post_z(const Params& p, int layer) {
;     ...
;         zr[(size_t)i * ZS + colbase + lane] = f2bf(v[i] * rs * gv);
	v_mul_f32_e32 v137, v122, v137
	v_mul_f32_e32 v138, v122, v138
	v_mul_f32_e32 v139, v122, v139
	v_mul_f32_e32 v140, v122, v140
	v_mul_f32_e32 v141, v122, v141
	v_mul_f32_e32 v142, v122, v142
	v_mul_f32_e32 v143, v122, v143
	v_mul_f32_e32 v144, v122, v144
	v_mul_f32_e32 v145, v122, v145
	v_mul_f32_e32 v146, v122, v146
	v_mul_f32_e32 v147, v122, v147
	v_mul_f32_e32 v148, v122, v148
	v_mul_f32_e32 v149, v122, v149
	v_mul_f32_e32 v150, v122, v150
	v_mul_f32_e32 v151, v122, v151
	v_mul_f32_e32 v152, v122, v152
	v_mul_f32_e32 v153, v122, v153
	v_mul_f32_e32 v154, v122, v154
	v_mul_f32_e32 v155, v122, v155
	v_mul_f32_e32 v156, v122, v156
	v_mul_f32_e32 v157, v122, v157
	v_mul_f32_e32 v158, v122, v158
	v_cvt_pk_bf16_f32 v127, v127, s0
	v_cvt_pk_bf16_f32 v128, v128, s0
	v_cvt_pk_bf16_f32 v129, v129, s0
	v_cvt_pk_bf16_f32 v130, v130, s0
	v_cvt_pk_bf16_f32 v131, v131, s0
	v_cvt_pk_bf16_f32 v132, v132, s0
	v_cvt_pk_bf16_f32 v133, v133, s0
	v_cvt_pk_bf16_f32 v134, v134, s0
	v_cvt_pk_bf16_f32 v135, v135, s0
	v_cvt_pk_bf16_f32 v136, v136, s0
	v_cvt_pk_bf16_f32 v137, v137, s0
	v_cvt_pk_bf16_f32 v138, v138, s0
	v_cvt_pk_bf16_f32 v139, v139, s0
	v_cvt_pk_bf16_f32 v140, v140, s0
	v_cvt_pk_bf16_f32 v141, v141, s0
	v_cvt_pk_bf16_f32 v142, v142, s0
	v_cvt_pk_bf16_f32 v143, v143, s0
	v_cvt_pk_bf16_f32 v144, v144, s0
	v_cvt_pk_bf16_f32 v145, v145, s0
	v_cvt_pk_bf16_f32 v146, v146, s0
	v_cvt_pk_bf16_f32 v147, v147, s0
	v_cvt_pk_bf16_f32 v148, v148, s0
	v_cvt_pk_bf16_f32 v149, v149, s0
	v_cvt_pk_bf16_f32 v150, v150, s0
	v_cvt_pk_bf16_f32 v151, v151, s0
	v_cvt_pk_bf16_f32 v152, v152, s0
	v_cvt_pk_bf16_f32 v153, v153, s0
	v_cvt_pk_bf16_f32 v154, v154, s0
	v_cvt_pk_bf16_f32 v155, v155, s0
	v_cvt_pk_bf16_f32 v156, v156, s0
	v_cvt_pk_bf16_f32 v157, v157, s0
	v_cvt_pk_bf16_f32 v158, v158, s0
	global_store_short v[118:119], v127, off
	v_lshl_add_u64 v[118:119], v[118:119], 0, s[98:99]
	global_store_short v[118:119], v128, off
	v_lshl_add_u64 v[118:119], v[118:119], 0, s[98:99]
	global_store_short v[118:119], v129, off
	v_lshl_add_u64 v[118:119], v[118:119], 0, s[98:99]
	global_store_short v[118:119], v130, off
	v_lshl_add_u64 v[118:119], v[118:119], 0, s[98:99]
	global_store_short v[118:119], v131, off
	v_lshl_add_u64 v[118:119], v[118:119], 0, s[98:99]
	global_store_short v[118:119], v132, off
	v_lshl_add_u64 v[118:119], v[118:119], 0, s[98:99]
	global_store_short v[118:119], v133, off
	v_lshl_add_u64 v[118:119], v[118:119], 0, s[98:99]
	global_store_short v[118:119], v134, off
	v_lshl_add_u64 v[118:119], v[118:119], 0, s[98:99]
	global_store_short v[118:119], v135, off
	v_lshl_add_u64 v[118:119], v[118:119], 0, s[98:99]
	global_store_short v[118:119], v136, off
	v_lshl_add_u64 v[118:119], v[118:119], 0, s[98:99]
	global_store_short v[118:119], v137, off
	v_lshl_add_u64 v[118:119], v[118:119], 0, s[98:99]
	global_store_short v[118:119], v138, off
	v_lshl_add_u64 v[118:119], v[118:119], 0, s[98:99]
	global_store_short v[118:119], v139, off
	v_lshl_add_u64 v[118:119], v[118:119], 0, s[98:99]
	global_store_short v[118:119], v140, off
	v_lshl_add_u64 v[118:119], v[118:119], 0, s[98:99]
	global_store_short v[118:119], v141, off
	v_lshl_add_u64 v[118:119], v[118:119], 0, s[98:99]
	global_store_short v[118:119], v142, off
	v_lshl_add_u64 v[118:119], v[118:119], 0, s[98:99]
	global_store_short v[118:119], v143, off
	v_lshl_add_u64 v[118:119], v[118:119], 0, s[98:99]
	global_store_short v[118:119], v144, off
	v_lshl_add_u64 v[118:119], v[118:119], 0, s[98:99]
	global_store_short v[118:119], v145, off
	v_lshl_add_u64 v[118:119], v[118:119], 0, s[98:99]
	global_store_short v[118:119], v146, off
	v_lshl_add_u64 v[118:119], v[118:119], 0, s[98:99]
	global_store_short v[118:119], v147, off
	v_lshl_add_u64 v[118:119], v[118:119], 0, s[98:99]
	global_store_short v[118:119], v148, off
	v_lshl_add_u64 v[118:119], v[118:119], 0, s[98:99]
	global_store_short v[118:119], v149, off
	v_lshl_add_u64 v[118:119], v[118:119], 0, s[98:99]
	global_store_short v[118:119], v150, off
	v_lshl_add_u64 v[118:119], v[118:119], 0, s[98:99]
	global_store_short v[118:119], v151, off
	v_lshl_add_u64 v[118:119], v[118:119], 0, s[98:99]
	global_store_short v[118:119], v152, off
	v_lshl_add_u64 v[118:119], v[118:119], 0, s[98:99]
	global_store_short v[118:119], v153, off
	v_lshl_add_u64 v[118:119], v[118:119], 0, s[98:99]
	global_store_short v[118:119], v154, off
	v_lshl_add_u64 v[118:119], v[118:119], 0, s[98:99]
	global_store_short v[118:119], v155, off
	v_lshl_add_u64 v[118:119], v[118:119], 0, s[98:99]
	global_store_short v[118:119], v156, off
	v_lshl_add_u64 v[118:119], v[118:119], 0, s[98:99]
	global_store_short v[118:119], v157, off
	v_lshl_add_u64 v[118:119], v[118:119], 0, s[98:99]
	global_store_short v[118:119], v158, off
	v_lshl_add_u64 v[118:119], v[118:119], 0, s[98:99]
